# hidden activations H in a line-strided block layout: every 128-byte line is written in full by one store instruction, the 8 lines of a block lie 16 KiB apart; P7 loader offsets and k-step constants to
# baseline (speedup 1.0000x reference)
.LBB0_647:
	s_or_b64 exec, exec, s[0:1]
	s_add_u32 s3, s72, 0xa00000
	s_addc_u32 s26, s73, 0
	s_cmpk_lt_i32 s2, 0x400
	s_cselect_b64 s[0:1], -1, 0
	v_writelane_b32 v243, s0, 14
	s_ashr_i32 s27, s2, 31
	s_mul_i32 s29, s75, s74
	v_writelane_b32 v243, s1, 15
	s_lshr_b32 s0, s27, 29
	s_add_i32 s0, s2, s0
	s_ashr_i32 s4, s0, 3
	s_and_b32 s0, s0, -8
	s_sub_i32 s5, s2, s0
	s_lshl_b32 s6, s5, 7
	s_ashr_i32 s75, s74, 31
	s_add_u32 s50, s72, 0x200
	s_addc_u32 s51, s73, 0
	s_add_u32 s52, s72, 0x1000
	s_addc_u32 s53, s73, 0
	s_add_u32 s54, s72, 0x1100
	s_addc_u32 s55, s73, 0
	s_add_u32 s56, s72, 0x1200
	s_addc_u32 s57, s73, 0
	s_add_u32 s58, s72, 0x1300
	s_addc_u32 s59, s73, 0
	s_cmp_eq_u32 s33, 15
	s_cselect_b64 s[0:1], -1, 0
	v_writelane_b32 v243, s0, 16
	s_cmp_eq_u32 s33, 14
	v_lshl_add_u64 v[0:1], v[0:1], 2, s[72:73]
	v_writelane_b32 v243, s1, 17
	s_cselect_b64 s[0:1], -1, 0
	v_writelane_b32 v243, s0, 18
	s_cmp_eq_u32 s33, 13
	s_mul_i32 s8, s5, 0x81
	v_writelane_b32 v243, s1, 19
	s_cselect_b64 s[0:1], -1, 0
	v_writelane_b32 v243, s0, 20
	s_cmp_eq_u32 s33, 12
	s_mul_i32 s29, s29, s89
	v_writelane_b32 v243, s1, 21
	s_cselect_b64 s[0:1], -1, 0
	v_writelane_b32 v243, s0, 22
	s_cmp_eq_u32 s33, 11
	v_mov_b32_e32 v133, 0
	v_writelane_b32 v243, s1, 23
	s_cselect_b64 s[0:1], -1, 0
	v_writelane_b32 v243, s0, 24
	s_cmp_eq_u32 s33, 10
	v_mov_b32_e32 v148, 0x358637bd
	v_writelane_b32 v243, s1, 25
	s_cselect_b64 s[0:1], -1, 0
	v_writelane_b32 v243, s0, 26
	s_cmp_eq_u32 s33, 9
	v_mov_b32_e32 v149, 1
	v_writelane_b32 v243, s1, 27
	s_cselect_b64 s[0:1], -1, 0
	v_writelane_b32 v243, s0, 28
	s_cmp_eq_u32 s33, 8
	v_mov_b64_e32 v[134:135], 0x400
	v_writelane_b32 v243, s1, 29
	s_cselect_b64 s[0:1], -1, 0
	v_writelane_b32 v243, s0, 30
	s_cmp_eq_u32 s33, 7
	v_mov_b64_e32 v[136:137], 0x3ff
	v_writelane_b32 v243, s1, 31
	s_cselect_b64 s[0:1], -1, 0
	v_writelane_b32 v243, s0, 32
	s_cmp_eq_u32 s33, 6
	v_mov_b64_e32 v[138:139], 0x100
	v_writelane_b32 v243, s1, 33
	s_cselect_b64 s[0:1], -1, 0
	v_writelane_b32 v243, s0, 34
	s_cmp_eq_u32 s33, 5
	v_mov_b64_e32 v[140:141], 0xff
	v_writelane_b32 v243, s1, 35
	s_cselect_b64 s[0:1], -1, 0
	v_writelane_b32 v243, s0, 36
	s_cmp_eq_u32 s33, 4
	s_mov_b64 s[70:71], -1
	v_writelane_b32 v243, s1, 37
	s_cselect_b64 s[0:1], -1, 0
	v_writelane_b32 v243, s0, 38
	s_cmp_eq_u32 s33, 3
	s_nop 0
	v_writelane_b32 v243, s1, 39
	s_cselect_b64 s[0:1], -1, 0
	v_writelane_b32 v243, s0, 40
	s_cmp_eq_u32 s33, 2
	s_barrier
	v_writelane_b32 v243, s1, 41
	s_cselect_b64 s[0:1], -1, 0
	v_writelane_b32 v243, s0, 42
	s_cmp_eq_u32 s33, 1
	s_nop 0
	v_writelane_b32 v243, s1, 43
	s_cselect_b64 s[0:1], -1, 0
	v_writelane_b32 v243, s0, 44
	s_cmp_eq_u32 s33, 0
	s_nop 0
	v_writelane_b32 v243, s1, 45
	s_cselect_b64 s[0:1], -1, 0
	v_writelane_b32 v243, s0, 46
	s_nop 1
	v_writelane_b32 v243, s1, 47
	s_add_u32 s0, s72, 0x3400
	s_addc_u32 s1, s73, 0
	s_add_u32 s62, s72, 0x3500
	s_addc_u32 s63, s73, 0
	v_writelane_b32 v243, s0, 48
	s_add_u32 s33, s72, 0x1200000
	s_addc_u32 s28, s73, 0
	v_writelane_b32 v243, s1, 49
	s_lshl_b32 s7, s5, 5
	s_mov_b64 s[0:1], 0x1400
	s_cmp_lt_i32 s5, 0
	v_lshl_add_u64 v[128:129], v[0:1], 0, s[0:1]
	s_mov_b64 s[0:1], 0x2400
	v_lshl_add_u64 v[130:131], v[0:1], 0, s[0:1]
	s_mul_i32 s5, s5, 33
	s_cselect_b32 s0, s8, s6
	s_cselect_b32 s5, s5, s7
	s_add_i32 s0, s0, s4
	s_ashr_i32 s1, s0, 31
	s_lshr_b32 s1, s1, 25
	s_add_i32 s1, s0, s1
	s_ashr_i32 s6, s1, 7
	s_and_b32 s1, s1, 0xff80
	s_sub_i32 s1, s0, s1
	s_bfe_i32 s0, s1, 0x80000
	s_bfe_u32 s0, s0, 0x3000c
	s_add_i32 s7, s1, s0
	s_bfe_i32 s0, s7, 0x80000
	s_and_b32 s7, s7, 0xf8
	s_sub_i32 s1, s1, s7
	s_lshl_b32 s6, s6, 3
	s_sext_i32_i8 s1, s1
	s_sext_i32_i16 s8, s0
	s_add_i32 s10, s6, s1
	s_lshr_b32 s0, s8, 3
	s_mov_b32 s6, s10
	s_ashr_i32 s11, s10, 31
	v_writelane_b32 v243, s6, 50
	s_bfe_i64 s[0:1], s[0:1], 0x100000
	s_ashr_i32 s91, s8, 3
	v_writelane_b32 v243, s7, 51
	s_lshl_b64 s[6:7], s[10:11], 19
	s_lshl_b64 s[0:1], s[0:1], 19
	s_add_u32 s68, s3, s0
	s_addc_u32 s69, s26, s1
	v_writelane_b32 v243, s6, 52
	s_add_u32 s0, s68, 0x40000
	s_addc_u32 s1, s69, 0
	v_writelane_b32 v243, s7, 53
	v_writelane_b32 v243, s0, 54
	s_nop 1
	v_writelane_b32 v243, s1, 55
	s_add_u32 s0, s68, 0x80
	s_addc_u32 s1, s69, 0
	v_writelane_b32 v243, s0, 56
	s_nop 1
	v_writelane_b32 v243, s1, 57
	s_add_u32 s0, s68, 0x40080
	s_addc_u32 s1, s69, 0
	v_writelane_b32 v243, s0, 58
	s_nop 1
	v_writelane_b32 v243, s1, 59
	s_add_i32 s0, s5, s4
	s_ashr_i32 s1, s0, 31
	s_lshr_b32 s1, s1, 27
	s_add_i32 s1, s0, s1
	s_ashr_i32 s4, s1, 5
	s_and_b32 s1, s1, 0xffe0
	s_sub_i32 s1, s0, s1
	s_bfe_i32 s0, s1, 0x80000
	s_bfe_u32 s0, s0, 0x3000c
	s_add_i32 s5, s1, s0
	s_bfe_i32 s0, s5, 0x80000
	s_and_b32 s5, s5, 0xf8
	s_sub_i32 s1, s1, s5
	s_lshl_b32 s4, s4, 3
	s_sext_i32_i16 s6, s0
	s_sext_i32_i8 s1, s1
	s_add_i32 s8, s4, s1
	s_ashr_i32 s1, s6, 3
	s_lshr_b32 s0, s6, 3
	v_writelane_b32 v243, s1, 60
	s_mov_b32 s4, s8
	s_ashr_i32 s9, s8, 31
	v_writelane_b32 v243, s4, 61
	s_bfe_i64 s[0:1], s[0:1], 0x100000
	s_lshl_b64 s[0:1], s[0:1], 21
	v_writelane_b32 v243, s5, 62
	s_lshl_b64 s[4:5], s[8:9], 21
	s_add_u32 s84, s33, s0
	s_addc_u32 s85, s28, s1
	s_add_u32 s0, s84, 0x100000
	s_addc_u32 s1, s85, 0
	s_add_u32 s88, s48, s4
	v_writelane_b32 v243, s0, 63
	s_addc_u32 s89, s49, s5
	s_nop 0
	v_writelane_b32 v242, s1, 0
	s_add_u32 s0, s88, 0x100000
	s_addc_u32 s1, s89, 0
	s_add_u32 s92, s84, 0x80
	s_addc_u32 s93, s85, 0
	s_add_u32 s94, s88, 0x100
	s_addc_u32 s95, s89, 0
	v_writelane_b32 v242, s0, 1
	s_add_u32 s96, s84, 0x100080
	s_addc_u32 s97, s85, 0
	v_writelane_b32 v242, s1, 2
	s_add_i32 s0, 0, 0x23fc0
	v_writelane_b32 v243, s0, 8
	s_add_i32 s0, 0, 0x23fc4
	v_writelane_b32 v242, s0, 3
	s_mov_b64 s[0:1], 0
	s_branch .LBB0_651

.LBB0_667:
	v_lshl_add_u32 v222, s77, 8, v154
	v_lshlrev_b32_e32 v223, 2, v222
	s_lshl_b32 s14, s77, 21
	s_lshl_b32 s15, s76, 10
	s_add_i32 s14, s14, s15
	v_and_b32_e32 v224, 1, v165
	v_lshlrev_b32_e32 v224, 6, v224
	v_and_b32_e32 v225, 0x30, v165
	v_or_b32_e32 v224, v224, v225
	v_and_b32_e32 v225, 8, v165
	v_lshlrev_b32_e32 v225, 2, v225
	v_xor_b32_e32 v224, v224, v225
	v_and_b32_e32 v225, 0xe, v165
	v_lshl_or_b32 v224, v225, 13, v224
	v_and_b32_e32 v225, 0xc0, v165
	v_lshl_or_b32 v224, v225, 1, v224
	v_and_b32_e32 v225, 0x100, v165
	v_lshl_or_b32 v224, v225, 11, v224
	v_add_u32_e32 v224, s14, v224
	v_add_u32_e32 v226, 0x200, v224
	v_fmamk_f32 v166, v248, 0x3a800000, v148
	v_rsq_f32_e32 v166, v166
	s_nop 0
	v_pk_mul_f32 v[124:125], v[124:125], v[166:167] op_sel_hi:[1,0]
	v_pk_mul_f32 v[126:127], v[126:127], v[166:167] op_sel_hi:[1,0]
	v_pk_mul_f32 v[120:121], v[120:121], v[166:167] op_sel_hi:[1,0]
	v_pk_mul_f32 v[122:123], v[122:123], v[166:167] op_sel_hi:[1,0]
	v_pk_mul_f32 v[116:117], v[116:117], v[166:167] op_sel_hi:[1,0]
	v_pk_mul_f32 v[118:119], v[118:119], v[166:167] op_sel_hi:[1,0]
	v_pk_mul_f32 v[112:113], v[112:113], v[166:167] op_sel_hi:[1,0]
	v_pk_mul_f32 v[114:115], v[114:115], v[166:167] op_sel_hi:[1,0]
	v_max_f32_e32 v124, 0, v124
	v_max_f32_e32 v125, 0, v125
	v_max_f32_e32 v126, 0, v126
	v_max_f32_e32 v127, 0, v127
	v_max_f32_e32 v120, 0, v120
	v_max_f32_e32 v121, 0, v121
	v_max_f32_e32 v122, 0, v122
	v_max_f32_e32 v123, 0, v123
	v_max_f32_e32 v116, 0, v116
	v_max_f32_e32 v117, 0, v117
	v_max_f32_e32 v118, 0, v118
	v_max_f32_e32 v119, 0, v119
	v_max_f32_e32 v112, 0, v112
	v_max_f32_e32 v113, 0, v113
	v_max_f32_e32 v114, 0, v114
	v_max_f32_e32 v115, 0, v115
	v_pk_mul_f32 v[124:125], v[124:125], v[124:125]
	v_pk_mul_f32 v[126:127], v[126:127], v[126:127]
	v_pk_mul_f32 v[120:121], v[120:121], v[120:121]
	v_pk_mul_f32 v[122:123], v[122:123], v[122:123]
	v_pk_mul_f32 v[116:117], v[116:117], v[116:117]
	v_pk_mul_f32 v[118:119], v[118:119], v[118:119]
	v_pk_mul_f32 v[112:113], v[112:113], v[112:113]
	v_pk_mul_f32 v[114:115], v[114:115], v[114:115]
	v_cvt_pk_bf16_f32 v124, v124, v125
	v_cvt_pk_bf16_f32 v125, v126, v127
	v_cvt_pk_bf16_f32 v126, v120, v121
	v_cvt_pk_bf16_f32 v127, v122, v123
	v_cvt_pk_bf16_f32 v116, v116, v117
	v_cvt_pk_bf16_f32 v117, v118, v119
	v_cvt_pk_bf16_f32 v118, v112, v113
	v_cvt_pk_bf16_f32 v119, v114, v115
	global_store_dwordx4 v224, v[124:127], s[48:49]
	global_store_dwordx4 v226, v[116:119], s[48:49]
	v_fmamk_f32 v168, v249, 0x3a800000, v148
	v_rsq_f32_e32 v168, v168
	s_nop 0
	v_pk_mul_f32 v[108:109], v[108:109], v[168:169] op_sel_hi:[1,0]
	v_pk_mul_f32 v[110:111], v[110:111], v[168:169] op_sel_hi:[1,0]
	v_pk_mul_f32 v[104:105], v[104:105], v[168:169] op_sel_hi:[1,0]
	v_pk_mul_f32 v[106:107], v[106:107], v[168:169] op_sel_hi:[1,0]
	v_pk_mul_f32 v[100:101], v[100:101], v[168:169] op_sel_hi:[1,0]
	v_pk_mul_f32 v[102:103], v[102:103], v[168:169] op_sel_hi:[1,0]
	v_pk_mul_f32 v[96:97], v[96:97], v[168:169] op_sel_hi:[1,0]
	v_pk_mul_f32 v[98:99], v[98:99], v[168:169] op_sel_hi:[1,0]
	v_max_f32_e32 v108, 0, v108
	v_max_f32_e32 v109, 0, v109
	v_max_f32_e32 v110, 0, v110
	v_max_f32_e32 v111, 0, v111
	v_max_f32_e32 v104, 0, v104
	v_max_f32_e32 v105, 0, v105
	v_max_f32_e32 v106, 0, v106
	v_max_f32_e32 v107, 0, v107
	v_max_f32_e32 v100, 0, v100
	v_max_f32_e32 v101, 0, v101
	v_max_f32_e32 v102, 0, v102
	v_max_f32_e32 v103, 0, v103
	v_max_f32_e32 v96, 0, v96
	v_max_f32_e32 v97, 0, v97
	v_max_f32_e32 v98, 0, v98
	v_max_f32_e32 v99, 0, v99
	v_pk_mul_f32 v[108:109], v[108:109], v[108:109]
	v_pk_mul_f32 v[110:111], v[110:111], v[110:111]
	v_pk_mul_f32 v[104:105], v[104:105], v[104:105]
	v_pk_mul_f32 v[106:107], v[106:107], v[106:107]
	v_pk_mul_f32 v[100:101], v[100:101], v[100:101]
	v_pk_mul_f32 v[102:103], v[102:103], v[102:103]
	v_pk_mul_f32 v[96:97], v[96:97], v[96:97]
	v_pk_mul_f32 v[98:99], v[98:99], v[98:99]
	v_cvt_pk_bf16_f32 v108, v108, v109
	v_cvt_pk_bf16_f32 v109, v110, v111
	v_cvt_pk_bf16_f32 v110, v104, v105
	v_cvt_pk_bf16_f32 v111, v106, v107
	v_cvt_pk_bf16_f32 v100, v100, v101
	v_cvt_pk_bf16_f32 v101, v102, v103
	v_cvt_pk_bf16_f32 v102, v96, v97
	v_cvt_pk_bf16_f32 v103, v98, v99
	v_add_u32_e32 v225, 0x20000, v224
	v_add_u32_e32 v227, 0x20000, v226
	global_store_dwordx4 v225, v[108:111], s[48:49]
	global_store_dwordx4 v227, v[100:103], s[48:49]
	v_fmamk_f32 v170, v250, 0x3a800000, v148
	v_rsq_f32_e32 v170, v170
	s_nop 0
	v_pk_mul_f32 v[92:93], v[92:93], v[170:171] op_sel_hi:[1,0]
	v_pk_mul_f32 v[94:95], v[94:95], v[170:171] op_sel_hi:[1,0]
	v_pk_mul_f32 v[88:89], v[88:89], v[170:171] op_sel_hi:[1,0]
	v_pk_mul_f32 v[90:91], v[90:91], v[170:171] op_sel_hi:[1,0]
	v_pk_mul_f32 v[84:85], v[84:85], v[170:171] op_sel_hi:[1,0]
	v_pk_mul_f32 v[86:87], v[86:87], v[170:171] op_sel_hi:[1,0]
	v_pk_mul_f32 v[80:81], v[80:81], v[170:171] op_sel_hi:[1,0]
	v_pk_mul_f32 v[82:83], v[82:83], v[170:171] op_sel_hi:[1,0]
	v_max_f32_e32 v92, 0, v92
	v_max_f32_e32 v93, 0, v93
	v_max_f32_e32 v94, 0, v94
	v_max_f32_e32 v95, 0, v95
	v_max_f32_e32 v88, 0, v88
	v_max_f32_e32 v89, 0, v89
	v_max_f32_e32 v90, 0, v90
	v_max_f32_e32 v91, 0, v91
	v_max_f32_e32 v84, 0, v84
	v_max_f32_e32 v85, 0, v85
	v_max_f32_e32 v86, 0, v86
	v_max_f32_e32 v87, 0, v87
	v_max_f32_e32 v80, 0, v80
	v_max_f32_e32 v81, 0, v81
	v_max_f32_e32 v82, 0, v82
	v_max_f32_e32 v83, 0, v83
	v_pk_mul_f32 v[92:93], v[92:93], v[92:93]
	v_pk_mul_f32 v[94:95], v[94:95], v[94:95]
	v_pk_mul_f32 v[88:89], v[88:89], v[88:89]
	v_pk_mul_f32 v[90:91], v[90:91], v[90:91]
	v_pk_mul_f32 v[84:85], v[84:85], v[84:85]
	v_pk_mul_f32 v[86:87], v[86:87], v[86:87]
	v_pk_mul_f32 v[80:81], v[80:81], v[80:81]
	v_pk_mul_f32 v[82:83], v[82:83], v[82:83]
	v_cvt_pk_bf16_f32 v92, v92, v93
	v_cvt_pk_bf16_f32 v93, v94, v95
	v_cvt_pk_bf16_f32 v94, v88, v89
	v_cvt_pk_bf16_f32 v95, v90, v91
	v_cvt_pk_bf16_f32 v84, v84, v85
	v_cvt_pk_bf16_f32 v85, v86, v87
	v_cvt_pk_bf16_f32 v86, v80, v81
	v_cvt_pk_bf16_f32 v87, v82, v83
	v_add_u32_e32 v225, 0x40000, v224
	v_add_u32_e32 v227, 0x40000, v226
	global_store_dwordx4 v225, v[92:95], s[48:49]
	global_store_dwordx4 v227, v[84:87], s[48:49]
	v_fmamk_f32 v172, v251, 0x3a800000, v148
	v_rsq_f32_e32 v172, v172
	s_nop 0
	v_pk_mul_f32 v[76:77], v[76:77], v[172:173] op_sel_hi:[1,0]
	v_pk_mul_f32 v[78:79], v[78:79], v[172:173] op_sel_hi:[1,0]
	v_pk_mul_f32 v[72:73], v[72:73], v[172:173] op_sel_hi:[1,0]
	v_pk_mul_f32 v[74:75], v[74:75], v[172:173] op_sel_hi:[1,0]
	v_pk_mul_f32 v[68:69], v[68:69], v[172:173] op_sel_hi:[1,0]
	v_pk_mul_f32 v[70:71], v[70:71], v[172:173] op_sel_hi:[1,0]
	v_pk_mul_f32 v[64:65], v[64:65], v[172:173] op_sel_hi:[1,0]
	v_pk_mul_f32 v[66:67], v[66:67], v[172:173] op_sel_hi:[1,0]
	v_max_f32_e32 v76, 0, v76
	v_max_f32_e32 v77, 0, v77
	v_max_f32_e32 v78, 0, v78
	v_max_f32_e32 v79, 0, v79
	v_max_f32_e32 v72, 0, v72
	v_max_f32_e32 v73, 0, v73
	v_max_f32_e32 v74, 0, v74
	v_max_f32_e32 v75, 0, v75
	v_max_f32_e32 v68, 0, v68
	v_max_f32_e32 v69, 0, v69
	v_max_f32_e32 v70, 0, v70
	v_max_f32_e32 v71, 0, v71
	v_max_f32_e32 v64, 0, v64
	v_max_f32_e32 v65, 0, v65
	v_max_f32_e32 v66, 0, v66
	v_max_f32_e32 v67, 0, v67
	v_pk_mul_f32 v[76:77], v[76:77], v[76:77]
	v_pk_mul_f32 v[78:79], v[78:79], v[78:79]
	v_pk_mul_f32 v[72:73], v[72:73], v[72:73]
	v_pk_mul_f32 v[74:75], v[74:75], v[74:75]
	v_pk_mul_f32 v[68:69], v[68:69], v[68:69]
	v_pk_mul_f32 v[70:71], v[70:71], v[70:71]
	v_pk_mul_f32 v[64:65], v[64:65], v[64:65]
	v_pk_mul_f32 v[66:67], v[66:67], v[66:67]
	v_cvt_pk_bf16_f32 v76, v76, v77
	v_cvt_pk_bf16_f32 v77, v78, v79
	v_cvt_pk_bf16_f32 v78, v72, v73
	v_cvt_pk_bf16_f32 v79, v74, v75
	v_cvt_pk_bf16_f32 v68, v68, v69
	v_cvt_pk_bf16_f32 v69, v70, v71
	v_cvt_pk_bf16_f32 v70, v64, v65
	v_cvt_pk_bf16_f32 v71, v66, v67
	v_add_u32_e32 v225, 0x60000, v224
	v_add_u32_e32 v227, 0x60000, v226
	global_store_dwordx4 v225, v[76:79], s[48:49]
	global_store_dwordx4 v227, v[68:71], s[48:49]
	v_fmamk_f32 v174, v252, 0x3a800000, v148
	v_rsq_f32_e32 v174, v174
	s_nop 0
	v_pk_mul_f32 v[60:61], v[60:61], v[174:175] op_sel_hi:[1,0]
	v_pk_mul_f32 v[62:63], v[62:63], v[174:175] op_sel_hi:[1,0]
	v_pk_mul_f32 v[56:57], v[56:57], v[174:175] op_sel_hi:[1,0]
	v_pk_mul_f32 v[58:59], v[58:59], v[174:175] op_sel_hi:[1,0]
	v_pk_mul_f32 v[52:53], v[52:53], v[174:175] op_sel_hi:[1,0]
	v_pk_mul_f32 v[54:55], v[54:55], v[174:175] op_sel_hi:[1,0]
	v_pk_mul_f32 v[48:49], v[48:49], v[174:175] op_sel_hi:[1,0]
	v_pk_mul_f32 v[50:51], v[50:51], v[174:175] op_sel_hi:[1,0]
	v_max_f32_e32 v60, 0, v60
	v_max_f32_e32 v61, 0, v61
	v_max_f32_e32 v62, 0, v62
	v_max_f32_e32 v63, 0, v63
	v_max_f32_e32 v56, 0, v56
	v_max_f32_e32 v57, 0, v57
	v_max_f32_e32 v58, 0, v58
	v_max_f32_e32 v59, 0, v59
	v_max_f32_e32 v52, 0, v52
	v_max_f32_e32 v53, 0, v53
	v_max_f32_e32 v54, 0, v54
	v_max_f32_e32 v55, 0, v55
	v_max_f32_e32 v48, 0, v48
	v_max_f32_e32 v49, 0, v49
	v_max_f32_e32 v50, 0, v50
	v_max_f32_e32 v51, 0, v51
	v_pk_mul_f32 v[60:61], v[60:61], v[60:61]
	v_pk_mul_f32 v[62:63], v[62:63], v[62:63]
	v_pk_mul_f32 v[56:57], v[56:57], v[56:57]
	v_pk_mul_f32 v[58:59], v[58:59], v[58:59]
	v_pk_mul_f32 v[52:53], v[52:53], v[52:53]
	v_pk_mul_f32 v[54:55], v[54:55], v[54:55]
	v_pk_mul_f32 v[48:49], v[48:49], v[48:49]
	v_pk_mul_f32 v[50:51], v[50:51], v[50:51]
	v_cvt_pk_bf16_f32 v60, v60, v61
	v_cvt_pk_bf16_f32 v61, v62, v63
	v_cvt_pk_bf16_f32 v62, v56, v57
	v_cvt_pk_bf16_f32 v63, v58, v59
	v_cvt_pk_bf16_f32 v52, v52, v53
	v_cvt_pk_bf16_f32 v53, v54, v55
	v_cvt_pk_bf16_f32 v54, v48, v49
	v_cvt_pk_bf16_f32 v55, v50, v51
	v_add_u32_e32 v225, 0x100000, v224
	v_add_u32_e32 v227, 0x100000, v226
	global_store_dwordx4 v225, v[60:63], s[48:49]
	global_store_dwordx4 v227, v[52:55], s[48:49]
	v_fmamk_f32 v176, v253, 0x3a800000, v148
	v_rsq_f32_e32 v176, v176
	s_nop 0
	v_pk_mul_f32 v[44:45], v[44:45], v[176:177] op_sel_hi:[1,0]
	v_pk_mul_f32 v[46:47], v[46:47], v[176:177] op_sel_hi:[1,0]
	v_pk_mul_f32 v[40:41], v[40:41], v[176:177] op_sel_hi:[1,0]
	v_pk_mul_f32 v[42:43], v[42:43], v[176:177] op_sel_hi:[1,0]
	v_pk_mul_f32 v[36:37], v[36:37], v[176:177] op_sel_hi:[1,0]
	v_pk_mul_f32 v[38:39], v[38:39], v[176:177] op_sel_hi:[1,0]
	v_pk_mul_f32 v[32:33], v[32:33], v[176:177] op_sel_hi:[1,0]
	v_pk_mul_f32 v[34:35], v[34:35], v[176:177] op_sel_hi:[1,0]
	v_max_f32_e32 v44, 0, v44
	v_max_f32_e32 v45, 0, v45
	v_max_f32_e32 v46, 0, v46
	v_max_f32_e32 v47, 0, v47
	v_max_f32_e32 v40, 0, v40
	v_max_f32_e32 v41, 0, v41
	v_max_f32_e32 v42, 0, v42
	v_max_f32_e32 v43, 0, v43
	v_max_f32_e32 v36, 0, v36
	v_max_f32_e32 v37, 0, v37
	v_max_f32_e32 v38, 0, v38
	v_max_f32_e32 v39, 0, v39
	v_max_f32_e32 v32, 0, v32
	v_max_f32_e32 v33, 0, v33
	v_max_f32_e32 v34, 0, v34
	v_max_f32_e32 v35, 0, v35
	v_pk_mul_f32 v[44:45], v[44:45], v[44:45]
	v_pk_mul_f32 v[46:47], v[46:47], v[46:47]
	v_pk_mul_f32 v[40:41], v[40:41], v[40:41]
	v_pk_mul_f32 v[42:43], v[42:43], v[42:43]
	v_pk_mul_f32 v[36:37], v[36:37], v[36:37]
	v_pk_mul_f32 v[38:39], v[38:39], v[38:39]
	v_pk_mul_f32 v[32:33], v[32:33], v[32:33]
	v_pk_mul_f32 v[34:35], v[34:35], v[34:35]
	v_cvt_pk_bf16_f32 v44, v44, v45
	v_cvt_pk_bf16_f32 v45, v46, v47
	v_cvt_pk_bf16_f32 v46, v40, v41
	v_cvt_pk_bf16_f32 v47, v42, v43
	v_cvt_pk_bf16_f32 v36, v36, v37
	v_cvt_pk_bf16_f32 v37, v38, v39
	v_cvt_pk_bf16_f32 v38, v32, v33
	v_cvt_pk_bf16_f32 v39, v34, v35
	v_add_u32_e32 v225, 0x120000, v224
	v_add_u32_e32 v227, 0x120000, v226
	global_store_dwordx4 v225, v[44:47], s[48:49]
	global_store_dwordx4 v227, v[36:39], s[48:49]
	v_fmamk_f32 v178, v254, 0x3a800000, v148
	v_rsq_f32_e32 v178, v178
	s_nop 0
	v_pk_mul_f32 v[28:29], v[28:29], v[178:179] op_sel_hi:[1,0]
	v_pk_mul_f32 v[30:31], v[30:31], v[178:179] op_sel_hi:[1,0]
	v_pk_mul_f32 v[24:25], v[24:25], v[178:179] op_sel_hi:[1,0]
	v_pk_mul_f32 v[26:27], v[26:27], v[178:179] op_sel_hi:[1,0]
	v_pk_mul_f32 v[20:21], v[20:21], v[178:179] op_sel_hi:[1,0]
	v_pk_mul_f32 v[22:23], v[22:23], v[178:179] op_sel_hi:[1,0]
	v_pk_mul_f32 v[16:17], v[16:17], v[178:179] op_sel_hi:[1,0]
	v_pk_mul_f32 v[18:19], v[18:19], v[178:179] op_sel_hi:[1,0]
	v_max_f32_e32 v28, 0, v28
	v_max_f32_e32 v29, 0, v29
	v_max_f32_e32 v30, 0, v30
	v_max_f32_e32 v31, 0, v31
	v_max_f32_e32 v24, 0, v24
	v_max_f32_e32 v25, 0, v25
	v_max_f32_e32 v26, 0, v26
	v_max_f32_e32 v27, 0, v27
	v_max_f32_e32 v20, 0, v20
	v_max_f32_e32 v21, 0, v21
	v_max_f32_e32 v22, 0, v22
	v_max_f32_e32 v23, 0, v23
	v_max_f32_e32 v16, 0, v16
	v_max_f32_e32 v17, 0, v17
	v_max_f32_e32 v18, 0, v18
	v_max_f32_e32 v19, 0, v19
	v_pk_mul_f32 v[28:29], v[28:29], v[28:29]
	v_pk_mul_f32 v[30:31], v[30:31], v[30:31]
	v_pk_mul_f32 v[24:25], v[24:25], v[24:25]
	v_pk_mul_f32 v[26:27], v[26:27], v[26:27]
	v_pk_mul_f32 v[20:21], v[20:21], v[20:21]
	v_pk_mul_f32 v[22:23], v[22:23], v[22:23]
	v_pk_mul_f32 v[16:17], v[16:17], v[16:17]
	v_pk_mul_f32 v[18:19], v[18:19], v[18:19]
	v_cvt_pk_bf16_f32 v28, v28, v29
	v_cvt_pk_bf16_f32 v29, v30, v31
	v_cvt_pk_bf16_f32 v30, v24, v25
	v_cvt_pk_bf16_f32 v31, v26, v27
	v_cvt_pk_bf16_f32 v20, v20, v21
	v_cvt_pk_bf16_f32 v21, v22, v23
	v_cvt_pk_bf16_f32 v22, v16, v17
	v_cvt_pk_bf16_f32 v23, v18, v19
	v_add_u32_e32 v225, 0x140000, v224
	v_add_u32_e32 v227, 0x140000, v226
	global_store_dwordx4 v225, v[28:31], s[48:49]
	global_store_dwordx4 v227, v[20:23], s[48:49]
	v_fmamk_f32 v180, v255, 0x3a800000, v148
	v_rsq_f32_e32 v180, v180
	s_nop 0
	v_pk_mul_f32 v[12:13], v[12:13], v[180:181] op_sel_hi:[1,0]
	v_pk_mul_f32 v[14:15], v[14:15], v[180:181] op_sel_hi:[1,0]
	v_pk_mul_f32 v[8:9], v[8:9], v[180:181] op_sel_hi:[1,0]
	v_pk_mul_f32 v[10:11], v[10:11], v[180:181] op_sel_hi:[1,0]
	v_pk_mul_f32 v[4:5], v[4:5], v[180:181] op_sel_hi:[1,0]
	v_pk_mul_f32 v[6:7], v[6:7], v[180:181] op_sel_hi:[1,0]
	v_pk_mul_f32 v[0:1], v[0:1], v[180:181] op_sel_hi:[1,0]
	v_pk_mul_f32 v[2:3], v[2:3], v[180:181] op_sel_hi:[1,0]
	v_max_f32_e32 v12, 0, v12
	v_max_f32_e32 v13, 0, v13
	v_max_f32_e32 v14, 0, v14
	v_max_f32_e32 v15, 0, v15
	v_max_f32_e32 v8, 0, v8
	v_max_f32_e32 v9, 0, v9
	v_max_f32_e32 v10, 0, v10
	v_max_f32_e32 v11, 0, v11
	v_max_f32_e32 v4, 0, v4
	v_max_f32_e32 v5, 0, v5
	v_max_f32_e32 v6, 0, v6
	v_max_f32_e32 v7, 0, v7
	v_max_f32_e32 v0, 0, v0
	v_max_f32_e32 v1, 0, v1
	v_max_f32_e32 v2, 0, v2
	v_max_f32_e32 v3, 0, v3
	v_pk_mul_f32 v[12:13], v[12:13], v[12:13]
	v_pk_mul_f32 v[14:15], v[14:15], v[14:15]
	v_pk_mul_f32 v[8:9], v[8:9], v[8:9]
	v_pk_mul_f32 v[10:11], v[10:11], v[10:11]
	v_pk_mul_f32 v[4:5], v[4:5], v[4:5]
	v_pk_mul_f32 v[6:7], v[6:7], v[6:7]
	v_pk_mul_f32 v[0:1], v[0:1], v[0:1]
	v_pk_mul_f32 v[2:3], v[2:3], v[2:3]
	v_cvt_pk_bf16_f32 v12, v12, v13
	v_cvt_pk_bf16_f32 v13, v14, v15
	v_cvt_pk_bf16_f32 v14, v8, v9
	v_cvt_pk_bf16_f32 v15, v10, v11
	v_cvt_pk_bf16_f32 v4, v4, v5
	v_cvt_pk_bf16_f32 v5, v6, v7
	v_cvt_pk_bf16_f32 v6, v0, v1
	v_cvt_pk_bf16_f32 v7, v2, v3
	v_add_u32_e32 v225, 0x160000, v224
	v_add_u32_e32 v227, 0x160000, v226
	global_store_dwordx4 v225, v[12:15], s[48:49]
	global_store_dwordx4 v227, v[4:7], s[48:49]
	s_mov_b32 s11, 0x160000
	s_andn2_b64 vcc, exec, s[36:37]
	s_mov_b64 s[14:15], -1
	s_cbranch_vccnz .LBB0_656
	s_andn2_b64 vcc, exec, s[4:5]
	s_cbranch_vccnz .LBB0_655
	s_barrier
	s_branch .LBB0_655

.LBB0_721:
	v_bfe_i32 v3, v0, 27, 1
	v_lshlrev_b32_e32 v1, 4, v0
	v_lshrrev_b32_e32 v3, 22, v3
	v_add_u32_e32 v3, v1, v3
	v_and_b32_e32 v3, 0xfffffc00, v3
	v_sub_u32_e32 v3, v1, v3
	v_ashrrev_i32_e32 v2, 31, v0
	v_lshrrev_b32_e32 v4, 4, v3
	v_lshrrev_b32_e32 v2, 26, v2
	v_bitop3_b32 v3, v4, v3, 32 bitop3:0x6c
	v_add_u32_e32 v2, v0, v2
	v_ashrrev_i32_e32 v5, 31, v3
	v_ashrrev_i32_e32 v2, 6, v2
	v_lshrrev_b32_e32 v5, 26, v5
	v_lshlrev_b32_e32 v4, 3, v2
	v_add_u32_e32 v5, v3, v5
	v_and_b32_e32 v4, -16, v4
	v_ashrrev_i32_e32 v6, 6, v5
	v_and_b32_e32 v5, 0xc0, v5
	v_add_u32_e32 v4, v6, v4
	v_sub_u32_e32 v3, v3, v5
	v_lshlrev_b32_e32 v2, 5, v2
	v_ashrrev_i16_sdwa v3, v149, sext(v3) dst_sel:DWORD dst_unused:UNUSED_PAD src0_sel:DWORD src1_sel:BYTE_0
	v_lshlrev_b32_e32 v5, 1, v4
	v_lshrrev_b32_e32 v7, 2, v4
	v_and_b32_e32 v6, 3, v6
	s_mov_b32 s0, 0x7ffe0
	v_and_b32_e32 v2, 32, v2
	v_bfe_i32 v3, v3, 0, 16
	v_and_b32_e32 v5, 24, v5
	v_and_b32_e32 v7, 4, v7
	v_and_or_b32 v6, v4, s0, v6
	v_or3_b32 v5, v6, v7, v5
	v_add_lshl_u32 v2, v2, v3, 1
	v_add_u32_e32 v1, 0x2000, v1
	v_lshl_add_u32 v132, v4, 13, v2
	v_lshl_add_u32 v146, v5, 13, v2
	v_ashrrev_i32_e32 v2, 31, v1
	v_lshrrev_b32_e32 v2, 22, v2
	v_add_u32_e32 v2, v1, v2
	v_ashrrev_i32_e32 v2, 10, v2
	v_mul_i32_i24_e32 v3, 0x400, v2
	v_sub_u32_e32 v1, v1, v3
	v_lshrrev_b32_e32 v3, 4, v1
	v_bitop3_b32 v1, v3, v1, 32 bitop3:0x6c
	v_ashrrev_i32_e32 v4, 31, v1
	v_lshrrev_b32_e32 v4, 26, v4
	v_lshlrev_b32_e32 v3, 3, v2
	v_add_u32_e32 v4, v1, v4
	v_and_b32_e32 v3, -16, v3
	v_ashrrev_i32_e32 v5, 6, v4
	v_and_b32_e32 v4, 0xc0, v4
	v_add_u32_e32 v3, v5, v3
	v_sub_u32_e32 v1, v1, v4
	v_and_b32_e32 v5, 3, v5
	s_ashr_i32 s8, s6, 6
	v_lshlrev_b32_e32 v2, 5, v2
	v_ashrrev_i16_sdwa v1, v149, sext(v1) dst_sel:DWORD dst_unused:UNUSED_PAD src0_sel:DWORD src1_sel:BYTE_0
	v_lshlrev_b32_e32 v4, 1, v3
	v_lshrrev_b32_e32 v6, 2, v3
	v_and_or_b32 v5, v3, s0, v5
	s_lshl_b32 s0, s8, 10
	v_and_b32_e32 v2, 32, v2
	v_bfe_i32 v1, v1, 0, 16
	v_and_b32_e32 v4, 24, v4
	v_and_b32_e32 v6, 4, v6
	s_add_i32 s38, s0, 0
	v_or3_b32 v4, v5, v6, v4
	v_add_lshl_u32 v1, v2, v1, 1
	s_add_i32 s39, s38, 0x10000
	s_mov_b32 s0, m0
	s_mov_b32 m0, s39
	s_nop 0
	global_load_lds_dwordx4 v146, s[84:85]
	s_mov_b32 m0, s0
	v_lshl_add_u32 v150, v4, 13, v1
	s_add_i32 s40, s38, 0x12000
	s_mov_b32 s0, m0
	s_mov_b32 m0, s40
	s_nop 0
	global_load_lds_dwordx4 v150, s[84:85]
	s_mov_b32 m0, s0
	v_readlane_b32 s10, v243, 63
	s_add_i32 s41, s38, 0x14000
	v_readlane_b32 s11, v242, 0
	s_mov_b32 s0, m0
	s_mov_b32 m0, s41
	s_nop 0
	global_load_lds_dwordx4 v146, s[10:11]
	s_mov_b32 m0, s0
	s_add_i32 s65, s38, 0x16000
	s_mov_b32 s0, m0
	s_mov_b32 m0, s65
	s_nop 0
	global_load_lds_dwordx4 v150, s[10:11]
	s_mov_b32 m0, s0
	v_and_b32_e32 v132, 7, v165
	v_lshlrev_b32_e32 v132, 4, v132
	v_and_b32_e32 v147, 0x38, v165
	v_lshl_or_b32 v132, v147, 11, v132
	v_and_b32_e32 v147, 0x40, v165
	v_lshl_or_b32 v132, v147, 1, v132
	v_and_b32_e32 v147, 0x180, v165
	v_lshl_or_b32 v132, v147, 10, v132
	v_add_u32_e32 v147, 0x80000, v132
	s_mov_b32 s0, m0
	s_mov_b32 m0, s38
	s_nop 0
	global_load_lds_dwordx4 v132, s[88:89]
	s_mov_b32 m0, s0
	s_add_i32 s35, s38, 0x2000
	s_mov_b32 s0, m0
	s_mov_b32 m0, s35
	s_nop 0
	global_load_lds_dwordx4 v147, s[88:89]
	s_mov_b32 m0, s0
	v_readlane_b32 s10, v242, 1
	s_add_i32 s30, s38, 0x4000
	v_readlane_b32 s11, v242, 2
	s_mov_b32 s0, m0
	s_mov_b32 m0, s30
	s_nop 0
	global_load_lds_dwordx4 v132, s[10:11]
	s_mov_b32 m0, s0
	s_ashr_i32 s7, s6, 8
	s_add_i32 s31, s38, 0x6000
	s_mov_b32 s0, m0
	s_mov_b32 m0, s31
	s_nop 0
	global_load_lds_dwordx4 v147, s[10:11]
	s_mov_b32 m0, s0
	s_cmp_eq_u32 s7, 1
	s_cselect_b64 s[0:1], -1, 0
	s_cmp_lg_u32 s7, 1
	s_cbranch_scc1 .LBB0_723
	s_barrier

.LBB0_732:
	s_ashr_i32 s11, s10, 31
	s_lshl_b64 s[12:13], s[10:11], 21
	s_add_u32 s12, s48, s12
	s_addc_u32 s13, s49, s13
	s_and_b64 s[14:15], s[36:37], exec
	s_cselect_b32 s11, s13, s17
	s_cselect_b32 vcc_lo, s12, s16
	s_ashr_i32 s9, s8, 31
	s_lshl_b64 s[14:15], s[8:9], 21
	s_add_u32 s14, s33, s14
	s_addc_u32 s15, s28, s15
	s_and_b64 s[20:21], s[36:37], exec
	s_cselect_b32 s9, s15, s19
	s_cselect_b32 s78, s14, s18
	s_add_u32 s79, s18, 0x100
	s_addc_u32 vcc_hi, s19, 0
	s_mov_b32 s80, -2
	v_add_u32_e32 v155, 0x10000, v153
	ds_read_b128 v[142:145], v155
	ds_read_b128 v[156:159], v155 offset:1024
	ds_read_b128 v[160:163], v155 offset:2048
	ds_read_b128 v[166:169], v155 offset:3072
	v_add_u32_e32 v155, 0x14000, v153
	ds_read_b128 v[170:173], v155
	ds_read_b128 v[174:177], v155 offset:1024
	ds_read_b128 v[178:181], v155 offset:2048
	ds_read_b128 v[182:185], v155 offset:3072
	s_add_u32 s18, s16, 0x200
	s_addc_u32 s19, s17, 0
	s_cmp_eq_u32 s80, 60
	s_cselect_b32 s24, vcc_lo, s18
	s_cselect_b32 s25, s11, s19
	s_cselect_b32 s22, s78, s79
	s_cselect_b32 s23, s9, vcc_hi
	s_add_u32 s20, s24, 0x100
	s_addc_u32 s21, s25, 0
	ds_read_b128 v[186:189], v154
	ds_read_b128 v[190:193], v154 offset:1024
	ds_read_b128 v[194:197], v154 offset:2048
	ds_read_b128 v[198:201], v154 offset:3072
	ds_read_b128 v[202:205], v154 offset:4096
	ds_read_b128 v[206:209], v154 offset:5120
	ds_read_b128 v[210:213], v154 offset:6144
	ds_read_b128 v[214:217], v154 offset:7168
	s_add_u32 s16, s16, 0x100100
	s_addc_u32 s17, s17, 0
	s_mov_b32 s81, m0
	s_mov_b32 m0, s83
	s_nop 0
	global_load_lds_dwordx4 v132, s[16:17]
	s_mov_b32 m0, s81
	s_add_i32 s81, s38, 0xe000
	s_mov_b32 s86, m0
	s_mov_b32 m0, s81
	s_nop 0
	global_load_lds_dwordx4 v147, s[16:17]
	s_mov_b32 m0, s86
	s_waitcnt vmcnt(8)
	s_waitcnt lgkmcnt(0)
	s_barrier
	s_setprio 1
	s_waitcnt lgkmcnt(7)
	v_mfma_f32_16x16x32_bf16 v[124:127], v[142:145], v[186:189], 0
	v_mfma_f32_16x16x32_bf16 v[120:123], v[160:163], v[186:189], 0
	s_waitcnt lgkmcnt(5)
	v_mfma_f32_16x16x32_bf16 v[108:111], v[142:145], v[194:197], 0
	v_mfma_f32_16x16x32_bf16 v[104:107], v[160:163], v[194:197], 0
	s_waitcnt lgkmcnt(3)
	v_mfma_f32_16x16x32_bf16 v[92:95], v[142:145], v[202:205], 0
	v_mfma_f32_16x16x32_bf16 v[88:91], v[160:163], v[202:205], 0
	s_waitcnt lgkmcnt(1)
	v_mfma_f32_16x16x32_bf16 v[76:79], v[142:145], v[210:213], 0
	v_mfma_f32_16x16x32_bf16 v[72:75], v[160:163], v[210:213], 0
	v_mfma_f32_16x16x32_bf16 v[124:127], v[156:159], v[190:193], v[124:127]
	v_mfma_f32_16x16x32_bf16 v[120:123], v[166:169], v[190:193], v[120:123]
	v_mfma_f32_16x16x32_bf16 v[108:111], v[156:159], v[198:201], v[108:111]
	v_mfma_f32_16x16x32_bf16 v[104:107], v[166:169], v[198:201], v[104:107]
	v_mfma_f32_16x16x32_bf16 v[92:95], v[156:159], v[206:209], v[92:95]
	v_mfma_f32_16x16x32_bf16 v[88:91], v[166:169], v[206:209], v[88:91]
	s_waitcnt lgkmcnt(0)
	v_mfma_f32_16x16x32_bf16 v[76:79], v[156:159], v[214:217], v[76:79]
	v_mfma_f32_16x16x32_bf16 v[72:75], v[166:169], v[214:217], v[72:75]
	s_setprio 0
	s_setprio 1
	v_mfma_f32_16x16x32_bf16 v[116:119], v[170:173], v[186:189], 0
	v_mfma_f32_16x16x32_bf16 v[112:115], v[178:181], v[186:189], 0
	v_mfma_f32_16x16x32_bf16 v[100:103], v[170:173], v[194:197], 0
	v_mfma_f32_16x16x32_bf16 v[96:99], v[178:181], v[194:197], 0
	v_mfma_f32_16x16x32_bf16 v[84:87], v[170:173], v[202:205], 0
	v_mfma_f32_16x16x32_bf16 v[80:83], v[178:181], v[202:205], 0
	v_mfma_f32_16x16x32_bf16 v[68:71], v[170:173], v[210:213], 0
	v_mfma_f32_16x16x32_bf16 v[64:67], v[178:181], v[210:213], 0
	v_mfma_f32_16x16x32_bf16 v[116:119], v[174:177], v[190:193], v[116:119]
	v_mfma_f32_16x16x32_bf16 v[112:115], v[182:185], v[190:193], v[112:115]
	v_mfma_f32_16x16x32_bf16 v[100:103], v[174:177], v[198:201], v[100:103]
	v_mfma_f32_16x16x32_bf16 v[96:99], v[182:185], v[198:201], v[96:99]
	v_mfma_f32_16x16x32_bf16 v[84:87], v[174:177], v[206:209], v[84:87]
	v_mfma_f32_16x16x32_bf16 v[80:83], v[182:185], v[206:209], v[80:83]
	v_mfma_f32_16x16x32_bf16 v[68:71], v[174:177], v[214:217], v[68:71]
	v_mfma_f32_16x16x32_bf16 v[64:67], v[182:185], v[214:217], v[64:67]
	s_setprio 0
	s_barrier
	ds_read_b128 v[186:189], v154 offset:16384
	ds_read_b128 v[190:193], v154 offset:17408
	ds_read_b128 v[194:197], v154 offset:18432
	ds_read_b128 v[198:201], v154 offset:19456
	ds_read_b128 v[202:205], v154 offset:20480
	ds_read_b128 v[206:209], v154 offset:21504
	ds_read_b128 v[210:213], v154 offset:22528
	ds_read_b128 v[214:217], v154 offset:23552
	s_mov_b32 s16, m0
	s_mov_b32 m0, s39
	s_nop 0
	global_load_lds_dwordx4 v146, s[22:23]
	s_mov_b32 m0, s16
	s_nop 0
	s_mov_b32 s16, m0
	s_mov_b32 m0, s40
	s_nop 0
	global_load_lds_dwordx4 v150, s[22:23]
	s_mov_b32 m0, s16
	s_add_u32 s16, s22, 0x100000
	s_addc_u32 s17, s23, 0
	s_mov_b32 s81, m0
	s_mov_b32 m0, s41
	s_nop 0
	global_load_lds_dwordx4 v146, s[16:17]
	s_mov_b32 m0, s81
	s_nop 0
	s_mov_b32 s81, m0
	s_mov_b32 m0, s65
	s_nop 0
	global_load_lds_dwordx4 v150, s[16:17]
	s_mov_b32 m0, s81
	s_mov_b32 s16, m0
	s_mov_b32 m0, s38
	s_nop 0
	global_load_lds_dwordx4 v132, s[24:25]
	s_mov_b32 m0, s16
	s_nop 0
	s_mov_b32 s16, m0
	s_mov_b32 m0, s35
	s_nop 0
	global_load_lds_dwordx4 v147, s[24:25]
	s_mov_b32 m0, s16
	s_waitcnt vmcnt(8)
	s_waitcnt lgkmcnt(0)
	s_barrier
	s_setprio 1
	s_waitcnt lgkmcnt(7)
	v_mfma_f32_16x16x32_bf16 v[60:63], v[142:145], v[186:189], 0
	v_mfma_f32_16x16x32_bf16 v[56:59], v[160:163], v[186:189], 0
	s_waitcnt lgkmcnt(5)
	v_mfma_f32_16x16x32_bf16 v[44:47], v[142:145], v[194:197], 0
	v_mfma_f32_16x16x32_bf16 v[40:43], v[160:163], v[194:197], 0
	s_waitcnt lgkmcnt(3)
	v_mfma_f32_16x16x32_bf16 v[28:31], v[142:145], v[202:205], 0
	v_mfma_f32_16x16x32_bf16 v[24:27], v[160:163], v[202:205], 0
	s_waitcnt lgkmcnt(1)
	v_mfma_f32_16x16x32_bf16 v[12:15], v[142:145], v[210:213], 0
	v_mfma_f32_16x16x32_bf16 v[8:11], v[160:163], v[210:213], 0
	v_mfma_f32_16x16x32_bf16 v[60:63], v[156:159], v[190:193], v[60:63]
	v_mfma_f32_16x16x32_bf16 v[56:59], v[166:169], v[190:193], v[56:59]
	v_mfma_f32_16x16x32_bf16 v[44:47], v[156:159], v[198:201], v[44:47]
	v_mfma_f32_16x16x32_bf16 v[40:43], v[166:169], v[198:201], v[40:43]
	v_mfma_f32_16x16x32_bf16 v[28:31], v[156:159], v[206:209], v[28:31]
	v_mfma_f32_16x16x32_bf16 v[24:27], v[166:169], v[206:209], v[24:27]
	s_waitcnt lgkmcnt(0)
	v_mfma_f32_16x16x32_bf16 v[12:15], v[156:159], v[214:217], v[12:15]
	v_mfma_f32_16x16x32_bf16 v[8:11], v[166:169], v[214:217], v[8:11]
	s_setprio 0
	s_setprio 1
	v_mfma_f32_16x16x32_bf16 v[52:55], v[170:173], v[186:189], 0
	v_mfma_f32_16x16x32_bf16 v[48:51], v[178:181], v[186:189], 0
	v_mfma_f32_16x16x32_bf16 v[36:39], v[170:173], v[194:197], 0
	v_mfma_f32_16x16x32_bf16 v[32:35], v[178:181], v[194:197], 0
	v_mfma_f32_16x16x32_bf16 v[20:23], v[170:173], v[202:205], 0
	v_mfma_f32_16x16x32_bf16 v[16:19], v[178:181], v[202:205], 0
	v_mfma_f32_16x16x32_bf16 v[4:7], v[170:173], v[210:213], 0
	v_mfma_f32_16x16x32_bf16 v[0:3], v[178:181], v[210:213], 0
	v_mfma_f32_16x16x32_bf16 v[52:55], v[174:177], v[190:193], v[52:55]
	v_mfma_f32_16x16x32_bf16 v[48:51], v[182:185], v[190:193], v[48:51]
	v_mfma_f32_16x16x32_bf16 v[36:39], v[174:177], v[198:201], v[36:39]
	v_mfma_f32_16x16x32_bf16 v[32:35], v[182:185], v[198:201], v[32:35]
	v_mfma_f32_16x16x32_bf16 v[20:23], v[174:177], v[206:209], v[20:23]
	v_mfma_f32_16x16x32_bf16 v[16:19], v[182:185], v[206:209], v[16:19]
	v_mfma_f32_16x16x32_bf16 v[4:7], v[174:177], v[214:217], v[4:7]
	v_mfma_f32_16x16x32_bf16 v[0:3], v[182:185], v[214:217], v[0:3]
	s_setprio 0
	s_barrier
	v_add_u32_e32 v155, 0x18000, v153
	ds_read_b128 v[142:145], v155
	ds_read_b128 v[156:159], v155 offset:1024
	ds_read_b128 v[160:163], v155 offset:2048
	ds_read_b128 v[166:169], v155 offset:3072
	v_add_u32_e32 v155, 0x1c000, v153
	ds_read_b128 v[170:173], v155
	ds_read_b128 v[174:177], v155 offset:1024
	ds_read_b128 v[178:181], v155 offset:2048
	ds_read_b128 v[182:185], v155 offset:3072
	ds_read_b128 v[186:189], v154 offset:32768
	ds_read_b128 v[190:193], v154 offset:33792
	ds_read_b128 v[194:197], v154 offset:34816
	ds_read_b128 v[198:201], v154 offset:35840
	ds_read_b128 v[202:205], v154 offset:36864
	ds_read_b128 v[206:209], v154 offset:37888
	ds_read_b128 v[210:213], v154 offset:38912
	ds_read_b128 v[214:217], v154 offset:39936
	s_add_u32 s16, s24, 0x100000
	s_addc_u32 s17, s25, 0
	s_mov_b32 s24, m0
	s_mov_b32 m0, s30
	s_nop 0
	global_load_lds_dwordx4 v132, s[16:17]
	s_mov_b32 m0, s24
	s_nop 0
	s_mov_b32 s24, m0
	s_mov_b32 m0, s31
	s_nop 0
	global_load_lds_dwordx4 v147, s[16:17]
	s_mov_b32 m0, s24
	s_waitcnt vmcnt(8)
	s_waitcnt lgkmcnt(0)
	s_barrier
	s_setprio 1
	s_waitcnt lgkmcnt(7)
	v_mfma_f32_16x16x32_bf16 v[124:127], v[142:145], v[186:189], v[124:127]
	v_mfma_f32_16x16x32_bf16 v[120:123], v[160:163], v[186:189], v[120:123]
	s_waitcnt lgkmcnt(5)
	v_mfma_f32_16x16x32_bf16 v[108:111], v[142:145], v[194:197], v[108:111]
	v_mfma_f32_16x16x32_bf16 v[104:107], v[160:163], v[194:197], v[104:107]
	s_waitcnt lgkmcnt(3)
	v_mfma_f32_16x16x32_bf16 v[92:95], v[142:145], v[202:205], v[92:95]
	v_mfma_f32_16x16x32_bf16 v[88:91], v[160:163], v[202:205], v[88:91]
	s_waitcnt lgkmcnt(1)
	v_mfma_f32_16x16x32_bf16 v[76:79], v[142:145], v[210:213], v[76:79]
	v_mfma_f32_16x16x32_bf16 v[72:75], v[160:163], v[210:213], v[72:75]
	v_mfma_f32_16x16x32_bf16 v[124:127], v[156:159], v[190:193], v[124:127]
	v_mfma_f32_16x16x32_bf16 v[120:123], v[166:169], v[190:193], v[120:123]
	v_mfma_f32_16x16x32_bf16 v[108:111], v[156:159], v[198:201], v[108:111]
	v_mfma_f32_16x16x32_bf16 v[104:107], v[166:169], v[198:201], v[104:107]
	v_mfma_f32_16x16x32_bf16 v[92:95], v[156:159], v[206:209], v[92:95]
	v_mfma_f32_16x16x32_bf16 v[88:91], v[166:169], v[206:209], v[88:91]
	s_waitcnt lgkmcnt(0)
	v_mfma_f32_16x16x32_bf16 v[76:79], v[156:159], v[214:217], v[76:79]
	v_mfma_f32_16x16x32_bf16 v[72:75], v[166:169], v[214:217], v[72:75]
	s_setprio 0
	s_setprio 1
	v_mfma_f32_16x16x32_bf16 v[116:119], v[170:173], v[186:189], v[116:119]
	v_mfma_f32_16x16x32_bf16 v[112:115], v[178:181], v[186:189], v[112:115]
	v_mfma_f32_16x16x32_bf16 v[100:103], v[170:173], v[194:197], v[100:103]
	v_mfma_f32_16x16x32_bf16 v[96:99], v[178:181], v[194:197], v[96:99]
	v_mfma_f32_16x16x32_bf16 v[84:87], v[170:173], v[202:205], v[84:87]
	v_mfma_f32_16x16x32_bf16 v[80:83], v[178:181], v[202:205], v[80:83]
	v_mfma_f32_16x16x32_bf16 v[68:71], v[170:173], v[210:213], v[68:71]
	v_mfma_f32_16x16x32_bf16 v[64:67], v[178:181], v[210:213], v[64:67]
	v_mfma_f32_16x16x32_bf16 v[116:119], v[174:177], v[190:193], v[116:119]
	v_mfma_f32_16x16x32_bf16 v[112:115], v[182:185], v[190:193], v[112:115]
	v_mfma_f32_16x16x32_bf16 v[100:103], v[174:177], v[198:201], v[100:103]
	v_mfma_f32_16x16x32_bf16 v[96:99], v[182:185], v[198:201], v[96:99]
	v_mfma_f32_16x16x32_bf16 v[84:87], v[174:177], v[206:209], v[84:87]
	v_mfma_f32_16x16x32_bf16 v[80:83], v[182:185], v[206:209], v[80:83]
	v_mfma_f32_16x16x32_bf16 v[68:71], v[174:177], v[214:217], v[68:71]
	v_mfma_f32_16x16x32_bf16 v[64:67], v[182:185], v[214:217], v[64:67]
	s_setprio 0
	s_barrier
	ds_read_b128 v[186:189], v154 offset:49152
	ds_read_b128 v[190:193], v154 offset:50176
	ds_read_b128 v[194:197], v154 offset:51200
	ds_read_b128 v[198:201], v154 offset:52224
	ds_read_b128 v[202:205], v154 offset:53248
	ds_read_b128 v[206:209], v154 offset:54272
	ds_read_b128 v[210:213], v154 offset:55296
	ds_read_b128 v[214:217], v154 offset:56320
	s_add_u32 s16, s22, 0x80
	s_addc_u32 s17, s23, 0
	s_mov_b32 s24, m0
	s_mov_b32 m0, s64
	s_nop 0
	global_load_lds_dwordx4 v146, s[16:17]
	s_mov_b32 m0, s24
	s_nop 0
	s_mov_b32 s24, m0
	s_mov_b32 m0, s82
	s_nop 0
	global_load_lds_dwordx4 v150, s[16:17]
	s_mov_b32 m0, s24
	s_add_u32 s16, s22, 0x100080
	s_addc_u32 s17, s23, 0
	s_mov_b32 s22, m0
	s_mov_b32 m0, s66
	s_nop 0
	global_load_lds_dwordx4 v146, s[16:17]
	s_mov_b32 m0, s22
	s_nop 0
	s_mov_b32 s22, m0
	s_mov_b32 m0, s67
	s_nop 0
	global_load_lds_dwordx4 v150, s[16:17]
	s_mov_b32 m0, s22
	s_mov_b32 s16, m0
	s_mov_b32 m0, s44
	s_nop 0
	global_load_lds_dwordx4 v132, s[20:21]
	s_mov_b32 m0, s16
	s_nop 0
	s_mov_b32 s16, m0
	s_mov_b32 m0, s45
	s_nop 0
	global_load_lds_dwordx4 v147, s[20:21]
	s_mov_b32 m0, s16
	s_waitcnt vmcnt(8)
	s_waitcnt lgkmcnt(0)
	s_barrier
	s_setprio 1
	s_waitcnt lgkmcnt(7)
	v_mfma_f32_16x16x32_bf16 v[60:63], v[142:145], v[186:189], v[60:63]
	v_mfma_f32_16x16x32_bf16 v[56:59], v[160:163], v[186:189], v[56:59]
	s_waitcnt lgkmcnt(5)
	v_mfma_f32_16x16x32_bf16 v[44:47], v[142:145], v[194:197], v[44:47]
	v_mfma_f32_16x16x32_bf16 v[40:43], v[160:163], v[194:197], v[40:43]
	s_waitcnt lgkmcnt(3)
	v_mfma_f32_16x16x32_bf16 v[28:31], v[142:145], v[202:205], v[28:31]
	v_mfma_f32_16x16x32_bf16 v[24:27], v[160:163], v[202:205], v[24:27]
	s_waitcnt lgkmcnt(1)
	v_mfma_f32_16x16x32_bf16 v[12:15], v[142:145], v[210:213], v[12:15]
	v_mfma_f32_16x16x32_bf16 v[8:11], v[160:163], v[210:213], v[8:11]
	v_mfma_f32_16x16x32_bf16 v[60:63], v[156:159], v[190:193], v[60:63]
	v_mfma_f32_16x16x32_bf16 v[56:59], v[166:169], v[190:193], v[56:59]
	v_mfma_f32_16x16x32_bf16 v[44:47], v[156:159], v[198:201], v[44:47]
	v_mfma_f32_16x16x32_bf16 v[40:43], v[166:169], v[198:201], v[40:43]
	v_mfma_f32_16x16x32_bf16 v[28:31], v[156:159], v[206:209], v[28:31]
	v_mfma_f32_16x16x32_bf16 v[24:27], v[166:169], v[206:209], v[24:27]
	s_waitcnt lgkmcnt(0)
	v_mfma_f32_16x16x32_bf16 v[12:15], v[156:159], v[214:217], v[12:15]
	v_mfma_f32_16x16x32_bf16 v[8:11], v[166:169], v[214:217], v[8:11]
	s_setprio 0
	s_setprio 1
	v_mfma_f32_16x16x32_bf16 v[52:55], v[170:173], v[186:189], v[52:55]
	v_mfma_f32_16x16x32_bf16 v[48:51], v[178:181], v[186:189], v[48:51]
	v_mfma_f32_16x16x32_bf16 v[36:39], v[170:173], v[194:197], v[36:39]
	v_mfma_f32_16x16x32_bf16 v[32:35], v[178:181], v[194:197], v[32:35]
	v_mfma_f32_16x16x32_bf16 v[20:23], v[170:173], v[202:205], v[20:23]
	v_mfma_f32_16x16x32_bf16 v[16:19], v[178:181], v[202:205], v[16:19]
	v_mfma_f32_16x16x32_bf16 v[4:7], v[170:173], v[210:213], v[4:7]
	v_mfma_f32_16x16x32_bf16 v[0:3], v[178:181], v[210:213], v[0:3]
	v_mfma_f32_16x16x32_bf16 v[52:55], v[174:177], v[190:193], v[52:55]
	v_mfma_f32_16x16x32_bf16 v[48:51], v[182:185], v[190:193], v[48:51]
	v_mfma_f32_16x16x32_bf16 v[36:39], v[174:177], v[198:201], v[36:39]
	v_mfma_f32_16x16x32_bf16 v[32:35], v[182:185], v[198:201], v[32:35]
	v_mfma_f32_16x16x32_bf16 v[20:23], v[174:177], v[206:209], v[20:23]
	v_mfma_f32_16x16x32_bf16 v[16:19], v[182:185], v[206:209], v[16:19]
	v_mfma_f32_16x16x32_bf16 v[4:7], v[174:177], v[214:217], v[4:7]
	v_mfma_f32_16x16x32_bf16 v[0:3], v[182:185], v[214:217], v[0:3]
	s_setprio 0
	s_barrier
	s_add_i32 s80, s80, 2
	s_add_u32 s79, s79, 0x100
	s_addc_u32 vcc_hi, vcc_hi, 0
	s_cmp_gt_u32 s80, 61
	s_mov_b64 s[16:17], s[18:19]
	s_branch .LBB0_733
.LBB0_733:
	v_add_u32_e32 v155, 0x10000, v153
	ds_read_b128 v[142:145], v155
	ds_read_b128 v[156:159], v155 offset:1024
	ds_read_b128 v[160:163], v155 offset:2048
	ds_read_b128 v[166:169], v155 offset:3072
	v_add_u32_e32 v155, 0x14000, v153
	ds_read_b128 v[170:173], v155
	ds_read_b128 v[174:177], v155 offset:1024
	ds_read_b128 v[178:181], v155 offset:2048
	ds_read_b128 v[182:185], v155 offset:3072
	s_add_u32 s18, s16, 0x200
	s_addc_u32 s19, s17, 0
	s_cmp_eq_u32 s80, 60
	s_cselect_b32 s24, vcc_lo, s18
	s_cselect_b32 s25, s11, s19
	s_cselect_b32 s22, s78, s79
	s_cselect_b32 s23, s9, vcc_hi
	s_add_u32 s20, s24, 0x100
	s_addc_u32 s21, s25, 0
	ds_read_b128 v[186:189], v154
	ds_read_b128 v[190:193], v154 offset:1024
	ds_read_b128 v[194:197], v154 offset:2048
	ds_read_b128 v[198:201], v154 offset:3072
	ds_read_b128 v[202:205], v154 offset:4096
	ds_read_b128 v[206:209], v154 offset:5120
	ds_read_b128 v[210:213], v154 offset:6144
	ds_read_b128 v[214:217], v154 offset:7168
	s_add_u32 s16, s16, 0x100100
	s_addc_u32 s17, s17, 0
	s_mov_b32 s81, m0
	s_mov_b32 m0, s83
	s_nop 0
	global_load_lds_dwordx4 v132, s[16:17]
	s_mov_b32 m0, s81
	s_add_i32 s81, s38, 0xe000
	s_mov_b32 s86, m0
	s_mov_b32 m0, s81
	s_nop 0
	global_load_lds_dwordx4 v147, s[16:17]
	s_mov_b32 m0, s86
	s_waitcnt vmcnt(8)
	s_waitcnt lgkmcnt(0)
	s_barrier
	s_setprio 1
	s_waitcnt lgkmcnt(7)
	v_mfma_f32_16x16x32_bf16 v[124:127], v[142:145], v[186:189], v[124:127]
	v_mfma_f32_16x16x32_bf16 v[120:123], v[160:163], v[186:189], v[120:123]
	s_waitcnt lgkmcnt(5)
	v_mfma_f32_16x16x32_bf16 v[108:111], v[142:145], v[194:197], v[108:111]
	v_mfma_f32_16x16x32_bf16 v[104:107], v[160:163], v[194:197], v[104:107]
	s_waitcnt lgkmcnt(3)
	v_mfma_f32_16x16x32_bf16 v[92:95], v[142:145], v[202:205], v[92:95]
	v_mfma_f32_16x16x32_bf16 v[88:91], v[160:163], v[202:205], v[88:91]
	s_waitcnt lgkmcnt(1)
	v_mfma_f32_16x16x32_bf16 v[76:79], v[142:145], v[210:213], v[76:79]
	v_mfma_f32_16x16x32_bf16 v[72:75], v[160:163], v[210:213], v[72:75]
	v_mfma_f32_16x16x32_bf16 v[124:127], v[156:159], v[190:193], v[124:127]
	v_mfma_f32_16x16x32_bf16 v[120:123], v[166:169], v[190:193], v[120:123]
	v_mfma_f32_16x16x32_bf16 v[108:111], v[156:159], v[198:201], v[108:111]
	v_mfma_f32_16x16x32_bf16 v[104:107], v[166:169], v[198:201], v[104:107]
	v_mfma_f32_16x16x32_bf16 v[92:95], v[156:159], v[206:209], v[92:95]
	v_mfma_f32_16x16x32_bf16 v[88:91], v[166:169], v[206:209], v[88:91]
	s_waitcnt lgkmcnt(0)
	v_mfma_f32_16x16x32_bf16 v[76:79], v[156:159], v[214:217], v[76:79]
	v_mfma_f32_16x16x32_bf16 v[72:75], v[166:169], v[214:217], v[72:75]
	s_setprio 0
	s_setprio 1
	v_mfma_f32_16x16x32_bf16 v[116:119], v[170:173], v[186:189], v[116:119]
	v_mfma_f32_16x16x32_bf16 v[112:115], v[178:181], v[186:189], v[112:115]
	v_mfma_f32_16x16x32_bf16 v[100:103], v[170:173], v[194:197], v[100:103]
	v_mfma_f32_16x16x32_bf16 v[96:99], v[178:181], v[194:197], v[96:99]
	v_mfma_f32_16x16x32_bf16 v[84:87], v[170:173], v[202:205], v[84:87]
	v_mfma_f32_16x16x32_bf16 v[80:83], v[178:181], v[202:205], v[80:83]
	v_mfma_f32_16x16x32_bf16 v[68:71], v[170:173], v[210:213], v[68:71]
	v_mfma_f32_16x16x32_bf16 v[64:67], v[178:181], v[210:213], v[64:67]
	v_mfma_f32_16x16x32_bf16 v[116:119], v[174:177], v[190:193], v[116:119]
	v_mfma_f32_16x16x32_bf16 v[112:115], v[182:185], v[190:193], v[112:115]
	v_mfma_f32_16x16x32_bf16 v[100:103], v[174:177], v[198:201], v[100:103]
	v_mfma_f32_16x16x32_bf16 v[96:99], v[182:185], v[198:201], v[96:99]
	v_mfma_f32_16x16x32_bf16 v[84:87], v[174:177], v[206:209], v[84:87]
	v_mfma_f32_16x16x32_bf16 v[80:83], v[182:185], v[206:209], v[80:83]
	v_mfma_f32_16x16x32_bf16 v[68:71], v[174:177], v[214:217], v[68:71]
	v_mfma_f32_16x16x32_bf16 v[64:67], v[182:185], v[214:217], v[64:67]
	s_setprio 0
	s_barrier
	ds_read_b128 v[186:189], v154 offset:16384
	ds_read_b128 v[190:193], v154 offset:17408
	ds_read_b128 v[194:197], v154 offset:18432
	ds_read_b128 v[198:201], v154 offset:19456
	ds_read_b128 v[202:205], v154 offset:20480
	ds_read_b128 v[206:209], v154 offset:21504
	ds_read_b128 v[210:213], v154 offset:22528
	ds_read_b128 v[214:217], v154 offset:23552
	s_mov_b32 s16, m0
	s_mov_b32 m0, s39
	s_nop 0
	global_load_lds_dwordx4 v146, s[22:23]
	s_mov_b32 m0, s16
	s_nop 0
	s_mov_b32 s16, m0
	s_mov_b32 m0, s40
	s_nop 0
	global_load_lds_dwordx4 v150, s[22:23]
	s_mov_b32 m0, s16
	s_add_u32 s16, s22, 0x100000
	s_addc_u32 s17, s23, 0
	s_mov_b32 s81, m0
	s_mov_b32 m0, s41
	s_nop 0
	global_load_lds_dwordx4 v146, s[16:17]
	s_mov_b32 m0, s81
	s_nop 0
	s_mov_b32 s81, m0
	s_mov_b32 m0, s65
	s_nop 0
	global_load_lds_dwordx4 v150, s[16:17]
	s_mov_b32 m0, s81
	s_mov_b32 s16, m0
	s_mov_b32 m0, s38
	s_nop 0
	global_load_lds_dwordx4 v132, s[24:25]
	s_mov_b32 m0, s16
	s_nop 0
	s_mov_b32 s16, m0
	s_mov_b32 m0, s35
	s_nop 0
	global_load_lds_dwordx4 v147, s[24:25]
	s_mov_b32 m0, s16
	s_waitcnt vmcnt(8)
	s_waitcnt lgkmcnt(0)
	s_barrier
	s_setprio 1
	s_waitcnt lgkmcnt(7)
	v_mfma_f32_16x16x32_bf16 v[60:63], v[142:145], v[186:189], v[60:63]
	v_mfma_f32_16x16x32_bf16 v[56:59], v[160:163], v[186:189], v[56:59]
	s_waitcnt lgkmcnt(5)
	v_mfma_f32_16x16x32_bf16 v[44:47], v[142:145], v[194:197], v[44:47]
	v_mfma_f32_16x16x32_bf16 v[40:43], v[160:163], v[194:197], v[40:43]
	s_waitcnt lgkmcnt(3)
	v_mfma_f32_16x16x32_bf16 v[28:31], v[142:145], v[202:205], v[28:31]
	v_mfma_f32_16x16x32_bf16 v[24:27], v[160:163], v[202:205], v[24:27]
	s_waitcnt lgkmcnt(1)
	v_mfma_f32_16x16x32_bf16 v[12:15], v[142:145], v[210:213], v[12:15]
	v_mfma_f32_16x16x32_bf16 v[8:11], v[160:163], v[210:213], v[8:11]
	v_mfma_f32_16x16x32_bf16 v[60:63], v[156:159], v[190:193], v[60:63]
	v_mfma_f32_16x16x32_bf16 v[56:59], v[166:169], v[190:193], v[56:59]
	v_mfma_f32_16x16x32_bf16 v[44:47], v[156:159], v[198:201], v[44:47]
	v_mfma_f32_16x16x32_bf16 v[40:43], v[166:169], v[198:201], v[40:43]
	v_mfma_f32_16x16x32_bf16 v[28:31], v[156:159], v[206:209], v[28:31]
	v_mfma_f32_16x16x32_bf16 v[24:27], v[166:169], v[206:209], v[24:27]
	s_waitcnt lgkmcnt(0)
	v_mfma_f32_16x16x32_bf16 v[12:15], v[156:159], v[214:217], v[12:15]
	v_mfma_f32_16x16x32_bf16 v[8:11], v[166:169], v[214:217], v[8:11]
	s_setprio 0
	s_setprio 1
	v_mfma_f32_16x16x32_bf16 v[52:55], v[170:173], v[186:189], v[52:55]
	v_mfma_f32_16x16x32_bf16 v[48:51], v[178:181], v[186:189], v[48:51]
	v_mfma_f32_16x16x32_bf16 v[36:39], v[170:173], v[194:197], v[36:39]
	v_mfma_f32_16x16x32_bf16 v[32:35], v[178:181], v[194:197], v[32:35]
	v_mfma_f32_16x16x32_bf16 v[20:23], v[170:173], v[202:205], v[20:23]
	v_mfma_f32_16x16x32_bf16 v[16:19], v[178:181], v[202:205], v[16:19]
	v_mfma_f32_16x16x32_bf16 v[4:7], v[170:173], v[210:213], v[4:7]
	v_mfma_f32_16x16x32_bf16 v[0:3], v[178:181], v[210:213], v[0:3]
	v_mfma_f32_16x16x32_bf16 v[52:55], v[174:177], v[190:193], v[52:55]
	v_mfma_f32_16x16x32_bf16 v[48:51], v[182:185], v[190:193], v[48:51]
	v_mfma_f32_16x16x32_bf16 v[36:39], v[174:177], v[198:201], v[36:39]
	v_mfma_f32_16x16x32_bf16 v[32:35], v[182:185], v[198:201], v[32:35]
	v_mfma_f32_16x16x32_bf16 v[20:23], v[174:177], v[206:209], v[20:23]
	v_mfma_f32_16x16x32_bf16 v[16:19], v[182:185], v[206:209], v[16:19]
	v_mfma_f32_16x16x32_bf16 v[4:7], v[174:177], v[214:217], v[4:7]
	v_mfma_f32_16x16x32_bf16 v[0:3], v[182:185], v[214:217], v[0:3]
	s_setprio 0
	s_barrier
	v_add_u32_e32 v155, 0x18000, v153
	ds_read_b128 v[142:145], v155
	ds_read_b128 v[156:159], v155 offset:1024
	ds_read_b128 v[160:163], v155 offset:2048
	ds_read_b128 v[166:169], v155 offset:3072
	v_add_u32_e32 v155, 0x1c000, v153
	ds_read_b128 v[170:173], v155
	ds_read_b128 v[174:177], v155 offset:1024
	ds_read_b128 v[178:181], v155 offset:2048
	ds_read_b128 v[182:185], v155 offset:3072
	ds_read_b128 v[186:189], v154 offset:32768
	ds_read_b128 v[190:193], v154 offset:33792
	ds_read_b128 v[194:197], v154 offset:34816
	ds_read_b128 v[198:201], v154 offset:35840
	ds_read_b128 v[202:205], v154 offset:36864
	ds_read_b128 v[206:209], v154 offset:37888
	ds_read_b128 v[210:213], v154 offset:38912
	ds_read_b128 v[214:217], v154 offset:39936
	s_add_u32 s16, s24, 0x100000
	s_addc_u32 s17, s25, 0
	s_mov_b32 s24, m0
	s_mov_b32 m0, s30
	s_nop 0
	global_load_lds_dwordx4 v132, s[16:17]
	s_mov_b32 m0, s24
	s_nop 0
	s_mov_b32 s24, m0
	s_mov_b32 m0, s31
	s_nop 0
	global_load_lds_dwordx4 v147, s[16:17]
	s_mov_b32 m0, s24
	s_waitcnt vmcnt(8)
	s_waitcnt lgkmcnt(0)
	s_barrier
	s_setprio 1
	s_waitcnt lgkmcnt(7)
	v_mfma_f32_16x16x32_bf16 v[124:127], v[142:145], v[186:189], v[124:127]
	v_mfma_f32_16x16x32_bf16 v[120:123], v[160:163], v[186:189], v[120:123]
	s_waitcnt lgkmcnt(5)
	v_mfma_f32_16x16x32_bf16 v[108:111], v[142:145], v[194:197], v[108:111]
	v_mfma_f32_16x16x32_bf16 v[104:107], v[160:163], v[194:197], v[104:107]
	s_waitcnt lgkmcnt(3)
	v_mfma_f32_16x16x32_bf16 v[92:95], v[142:145], v[202:205], v[92:95]
	v_mfma_f32_16x16x32_bf16 v[88:91], v[160:163], v[202:205], v[88:91]
	s_waitcnt lgkmcnt(1)
	v_mfma_f32_16x16x32_bf16 v[76:79], v[142:145], v[210:213], v[76:79]
	v_mfma_f32_16x16x32_bf16 v[72:75], v[160:163], v[210:213], v[72:75]
	v_mfma_f32_16x16x32_bf16 v[124:127], v[156:159], v[190:193], v[124:127]
	v_mfma_f32_16x16x32_bf16 v[120:123], v[166:169], v[190:193], v[120:123]
	v_mfma_f32_16x16x32_bf16 v[108:111], v[156:159], v[198:201], v[108:111]
	v_mfma_f32_16x16x32_bf16 v[104:107], v[166:169], v[198:201], v[104:107]
	v_mfma_f32_16x16x32_bf16 v[92:95], v[156:159], v[206:209], v[92:95]
	v_mfma_f32_16x16x32_bf16 v[88:91], v[166:169], v[206:209], v[88:91]
	s_waitcnt lgkmcnt(0)
	v_mfma_f32_16x16x32_bf16 v[76:79], v[156:159], v[214:217], v[76:79]
	v_mfma_f32_16x16x32_bf16 v[72:75], v[166:169], v[214:217], v[72:75]
	s_setprio 0
	s_setprio 1
	v_mfma_f32_16x16x32_bf16 v[116:119], v[170:173], v[186:189], v[116:119]
	v_mfma_f32_16x16x32_bf16 v[112:115], v[178:181], v[186:189], v[112:115]
	v_mfma_f32_16x16x32_bf16 v[100:103], v[170:173], v[194:197], v[100:103]
	v_mfma_f32_16x16x32_bf16 v[96:99], v[178:181], v[194:197], v[96:99]
	v_mfma_f32_16x16x32_bf16 v[84:87], v[170:173], v[202:205], v[84:87]
	v_mfma_f32_16x16x32_bf16 v[80:83], v[178:181], v[202:205], v[80:83]
	v_mfma_f32_16x16x32_bf16 v[68:71], v[170:173], v[210:213], v[68:71]
	v_mfma_f32_16x16x32_bf16 v[64:67], v[178:181], v[210:213], v[64:67]
	v_mfma_f32_16x16x32_bf16 v[116:119], v[174:177], v[190:193], v[116:119]
	v_mfma_f32_16x16x32_bf16 v[112:115], v[182:185], v[190:193], v[112:115]
	v_mfma_f32_16x16x32_bf16 v[100:103], v[174:177], v[198:201], v[100:103]
	v_mfma_f32_16x16x32_bf16 v[96:99], v[182:185], v[198:201], v[96:99]
	v_mfma_f32_16x16x32_bf16 v[84:87], v[174:177], v[206:209], v[84:87]
	v_mfma_f32_16x16x32_bf16 v[80:83], v[182:185], v[206:209], v[80:83]
	v_mfma_f32_16x16x32_bf16 v[68:71], v[174:177], v[214:217], v[68:71]
	v_mfma_f32_16x16x32_bf16 v[64:67], v[182:185], v[214:217], v[64:67]
	s_setprio 0
	s_barrier
	ds_read_b128 v[186:189], v154 offset:49152
	ds_read_b128 v[190:193], v154 offset:50176
	ds_read_b128 v[194:197], v154 offset:51200
	ds_read_b128 v[198:201], v154 offset:52224
	ds_read_b128 v[202:205], v154 offset:53248
	ds_read_b128 v[206:209], v154 offset:54272
	ds_read_b128 v[210:213], v154 offset:55296
	ds_read_b128 v[214:217], v154 offset:56320
	s_add_u32 s16, s22, 0x80
	s_addc_u32 s17, s23, 0
	s_mov_b32 s24, m0
	s_mov_b32 m0, s64
	s_nop 0
	global_load_lds_dwordx4 v146, s[16:17]
	s_mov_b32 m0, s24
	s_nop 0
	s_mov_b32 s24, m0
	s_mov_b32 m0, s82
	s_nop 0
	global_load_lds_dwordx4 v150, s[16:17]
	s_mov_b32 m0, s24
	s_add_u32 s16, s22, 0x100080
	s_addc_u32 s17, s23, 0
	s_mov_b32 s22, m0
	s_mov_b32 m0, s66
	s_nop 0
	global_load_lds_dwordx4 v146, s[16:17]
	s_mov_b32 m0, s22
	s_nop 0
	s_mov_b32 s22, m0
	s_mov_b32 m0, s67
	s_nop 0
	global_load_lds_dwordx4 v150, s[16:17]
	s_mov_b32 m0, s22
	s_mov_b32 s16, m0
	s_mov_b32 m0, s44
	s_nop 0
	global_load_lds_dwordx4 v132, s[20:21]
	s_mov_b32 m0, s16
	s_nop 0
	s_mov_b32 s16, m0
	s_mov_b32 m0, s45
	s_nop 0
	global_load_lds_dwordx4 v147, s[20:21]
	s_mov_b32 m0, s16
	s_waitcnt vmcnt(8)
	s_waitcnt lgkmcnt(0)
	s_barrier
	s_setprio 1
	s_waitcnt lgkmcnt(7)
	v_mfma_f32_16x16x32_bf16 v[60:63], v[142:145], v[186:189], v[60:63]
	v_mfma_f32_16x16x32_bf16 v[56:59], v[160:163], v[186:189], v[56:59]
	s_waitcnt lgkmcnt(5)
	v_mfma_f32_16x16x32_bf16 v[44:47], v[142:145], v[194:197], v[44:47]
	v_mfma_f32_16x16x32_bf16 v[40:43], v[160:163], v[194:197], v[40:43]
	s_waitcnt lgkmcnt(3)
	v_mfma_f32_16x16x32_bf16 v[28:31], v[142:145], v[202:205], v[28:31]
	v_mfma_f32_16x16x32_bf16 v[24:27], v[160:163], v[202:205], v[24:27]
	s_waitcnt lgkmcnt(1)
	v_mfma_f32_16x16x32_bf16 v[12:15], v[142:145], v[210:213], v[12:15]
	v_mfma_f32_16x16x32_bf16 v[8:11], v[160:163], v[210:213], v[8:11]
	v_mfma_f32_16x16x32_bf16 v[60:63], v[156:159], v[190:193], v[60:63]
	v_mfma_f32_16x16x32_bf16 v[56:59], v[166:169], v[190:193], v[56:59]
	v_mfma_f32_16x16x32_bf16 v[44:47], v[156:159], v[198:201], v[44:47]
	v_mfma_f32_16x16x32_bf16 v[40:43], v[166:169], v[198:201], v[40:43]
	v_mfma_f32_16x16x32_bf16 v[28:31], v[156:159], v[206:209], v[28:31]
	v_mfma_f32_16x16x32_bf16 v[24:27], v[166:169], v[206:209], v[24:27]
	s_waitcnt lgkmcnt(0)
	v_mfma_f32_16x16x32_bf16 v[12:15], v[156:159], v[214:217], v[12:15]
	v_mfma_f32_16x16x32_bf16 v[8:11], v[166:169], v[214:217], v[8:11]
	s_setprio 0
	s_setprio 1
	v_mfma_f32_16x16x32_bf16 v[52:55], v[170:173], v[186:189], v[52:55]
	v_mfma_f32_16x16x32_bf16 v[48:51], v[178:181], v[186:189], v[48:51]
	v_mfma_f32_16x16x32_bf16 v[36:39], v[170:173], v[194:197], v[36:39]
	v_mfma_f32_16x16x32_bf16 v[32:35], v[178:181], v[194:197], v[32:35]
	v_mfma_f32_16x16x32_bf16 v[20:23], v[170:173], v[202:205], v[20:23]
	v_mfma_f32_16x16x32_bf16 v[16:19], v[178:181], v[202:205], v[16:19]
	v_mfma_f32_16x16x32_bf16 v[4:7], v[170:173], v[210:213], v[4:7]
	v_mfma_f32_16x16x32_bf16 v[0:3], v[178:181], v[210:213], v[0:3]
	v_mfma_f32_16x16x32_bf16 v[52:55], v[174:177], v[190:193], v[52:55]
	v_mfma_f32_16x16x32_bf16 v[48:51], v[182:185], v[190:193], v[48:51]
	v_mfma_f32_16x16x32_bf16 v[36:39], v[174:177], v[198:201], v[36:39]
	v_mfma_f32_16x16x32_bf16 v[32:35], v[182:185], v[198:201], v[32:35]
	v_mfma_f32_16x16x32_bf16 v[20:23], v[174:177], v[206:209], v[20:23]
	v_mfma_f32_16x16x32_bf16 v[16:19], v[182:185], v[206:209], v[16:19]
	v_mfma_f32_16x16x32_bf16 v[4:7], v[174:177], v[214:217], v[4:7]
	v_mfma_f32_16x16x32_bf16 v[0:3], v[182:185], v[214:217], v[0:3]
	s_setprio 0
	s_barrier
	s_add_i32 s80, s80, 2
	s_add_u32 s79, s79, 0x100
	s_addc_u32 vcc_hi, vcc_hi, 0
	s_cmp_gt_u32 s80, 61
	s_mov_b64 s[16:17], s[18:19]
	s_cbranch_scc0 .LBB0_733
	s_and_b64 vcc, exec, s[6:7]
	s_cbranch_vccz .LBB0_736
	s_barrier
